# RMSNorm row loops prefetch the next row into a second register set while the current row is processed
# baseline (speedup 1.0000x reference)
; __device__ __forceinline__ int TID() { int t = threadIdx.x; asm volatile("" : "+v"(t)); return t; }
; __device__ __forceinline__ int BID() { int t = blockIdx.x; asm volatile("" : "+s"(t)); return t; }
; __device__ __forceinline__ int NBLK() { int t = gridDim.x; asm volatile("" : "+s"(t)); return t; }
; __device__ void rmsnorm_phase(const float* __restrict__ x, const float* __restrict__ g, bf16_t* h, float* outf) {
;     const int lane = TID() & 63, gw = BID() * 8 + (TID() >> 6), nw = NBLK() * 8;
;     float4 gv[4];
; #pragma unroll
;     for (int i = 0; i < 4; ++i) gv[i] = ((const float4*)g)[lane + 64 * i];
;     for (int row = gw; row < T_; row += nw) {
;         const float4* xr = (const float4*)(x + (size_t)row * D_);
;         float4 v[4]; float ss = 0.f;
; #pragma unroll
;         for (int i = 0; i < 4; ++i) { v[i] = xr[lane + 64 * i]; ss += v[i].x * v[i].x + v[i].y * v[i].y + v[i].z * v[i].z + v[i].w * v[i].w; }
.LBB0_77:
	s_andn2_b64 vcc, exec, s[2:3]
	s_cbranch_vccnz .LBB0_113
	v_readlane_b32 s2, v254, 37
	s_cmp_gt_i32 s2, 10
	s_mov_b64 s[2:3], -1
	s_cbranch_scc0 .LBB0_83
	s_mov_b32 s4, 31
	v_mov_b32_e32 v0, v168
	s_mov_b32 s2, s73
	v_mov_b32_e32 v2, v168
	s_mov_b32 s6, s39
	v_ashrrev_i32_e32 v2, 6, v2
	s_waitcnt vmcnt(0)
	v_lshl_add_u32 v18, s2, 3, v2
	v_cmp_gt_i32_e32 vcc, s58, v18
	s_and_saveexec_b64 s[2:3], vcc
	s_cbranch_execz .LBB0_82
	s_ashr_i32 s5, s4, 31
	s_lshl_b64 s[4:5], s[4:5], 3
	s_add_u32 s4, s0, s4
	s_addc_u32 s5, s1, s5
	s_load_dwordx2 s[4:5], s[4:5], 0x0
	v_readlane_b32 s8, v254, 31
	v_readlane_b32 s9, v254, 32
	s_mov_b32 s10, s8
	s_ashr_i32 s11, s8, 31
	v_writelane_b32 v254, s8, 31
	v_and_b32_e32 v22, 63, v0
	v_lshlrev_b32_e32 v29, 4, v22
	v_writelane_b32 v254, s9, 32
	s_lshl_b64 s[8:9], s[10:11], 12
	s_waitcnt lgkmcnt(0)
	s_add_u32 s4, s4, s8
	s_addc_u32 s5, s5, s9
	global_load_dwordx4 v[2:5], v29, s[4:5]
	global_load_dwordx4 v[6:9], v29, s[4:5] offset:1024
	global_load_dwordx4 v[10:13], v29, s[4:5] offset:2048
	global_load_dwordx4 v[14:17], v29, s[4:5] offset:3072
	v_and_b32_e32 v0, 64, v174
	v_add_u32_e32 v19, 64, v0
	v_xor_b32_e32 v0, 32, v174
	v_cmp_lt_i32_e32 vcc, v0, v19
	v_xor_b32_e32 v20, 16, v174
	s_lshl_b32 s4, s6, 3
	v_cndmask_b32_e32 v0, v174, v0, vcc
	v_cmp_lt_i32_e32 vcc, v20, v19
	v_readlane_b32 s6, v254, 33
	v_readlane_b32 s7, v254, 34
	v_cndmask_b32_e32 v20, v174, v20, vcc
	v_lshlrev_b32_e32 v24, 2, v20
	v_xor_b32_e32 v20, 8, v174
	v_cmp_lt_i32_e32 vcc, v20, v19
	s_ashr_i32 s5, s4, 31
	v_lshlrev_b32_e32 v0, 2, v0
	v_cndmask_b32_e32 v20, v174, v20, vcc
	v_lshlrev_b32_e32 v25, 2, v20
	v_xor_b32_e32 v20, 4, v174
	v_cmp_lt_i32_e32 vcc, v20, v19
	s_lshl_b64 s[8:9], s[4:5], 12
	s_mov_b64 s[10:11], 0
	v_cndmask_b32_e32 v20, v174, v20, vcc
	v_lshlrev_b32_e32 v26, 2, v20
	v_xor_b32_e32 v20, 2, v174
	v_cmp_lt_i32_e32 vcc, v20, v19
	s_nop 1
	v_cndmask_b32_e32 v20, v174, v20, vcc
	v_lshlrev_b32_e32 v27, 2, v20
	v_xor_b32_e32 v20, 1, v174
	v_cmp_lt_i32_e32 vcc, v20, v19
	s_nop 1
	v_cndmask_b32_e32 v19, v174, v20, vcc
	v_lshlrev_b32_e32 v28, 2, v19
	v_ashrrev_i32_e32 v19, 31, v18
	v_lshlrev_b64 v[20:21], 11, v[18:19]
	v_lshl_or_b32 v20, v22, 3, v20
	v_lshlrev_b64 v[22:23], 12, v[18:19]
	v_or_b32_e32 v22, v22, v29
	v_lshl_add_u64 v[20:21], s[6:7], 0, v[20:21]
	s_lshl_b64 s[6:7], s[4:5], 11
	v_lshl_add_u64 v[22:23], s[78:79], 0, v[22:23]
	v_readfirstlane_b32 s5, v18
	global_load_dwordx4 v[30:33], v[22:23], off
	global_load_dwordx4 v[34:37], v[22:23], off offset:1024
	global_load_dwordx4 v[56:59], v[22:23], off offset:2048
	global_load_dwordx4 v[60:63], v[22:23], off offset:3072
	v_lshl_add_u64 v[22:23], v[22:23], 0, s[8:9]
.LBB0_81:
	v_add_u32_e32 v18, s4, v18
	s_add_i32 s5, s5, s4
	s_cmp_lt_i32 s5, s58
	s_cbranch_scc0 .Lrn81_nopf
	global_load_dwordx4 v[64:67], v[22:23], off
	global_load_dwordx4 v[68:71], v[22:23], off offset:1024
	global_load_dwordx4 v[72:75], v[22:23], off offset:2048
	global_load_dwordx4 v[76:79], v[22:23], off offset:3072
	v_lshl_add_u64 v[22:23], v[22:23], 0, s[8:9]
	s_waitcnt vmcnt(4)
	s_branch .Lrn81_go

; __device__ __forceinline__ unsigned cvt_pk_bf16(float lo, float hi) { const f32x2_t v = {lo, hi}; const bf16x2_t b = __builtin_convertvector(v, bf16x2_t); return __builtin_bit_cast(unsigned, b); }
; __device__ void rmsnorm_phase(const float* __restrict__ x, const float* __restrict__ g, bf16_t* h, float* outf) {
;     ...
;     for (int row = gw; row < T_; row += nw) {
;         const float4* xr = (const float4*)(x + (size_t)row * D_);
;         float4 v[4]; float ss = 0.f;
; #pragma unroll
;         for (int i = 0; i < 4; ++i) { v[i] = xr[lane + 64 * i]; ss += v[i].x * v[i].x + v[i].y * v[i].y + v[i].z * v[i].z + v[i].w * v[i].w; }
; #pragma unroll
;         for (int o = 32; o >= 1; o >>= 1) ss += __shfl_xor(ss, o);
;         const float rs = rsqrtf(ss * (1.0f / 1024.0f) + 1e-6f);
; #pragma unroll
;         for (int i = 0; i < 4; ++i) {
;             const float a = v[i].x * rs * gv[i].x, b = v[i].y * rs * gv[i].y, c = v[i].z * rs * gv[i].z, d = v[i].w * rs * gv[i].w;
;             if (outf) ((float4*)(outf + (size_t)row * D_))[lane + 64 * i] = make_float4(a, b, c, d);
;             else { u32x2 w; w.x = cvt_pk_bf16(a, b); w.y = cvt_pk_bf16(c, d); *(u32x2*)(h + (size_t)row * D_ + (lane + 64 * i) * 4) = w; }
;         }
.Lrn81_go:
	v_mov_b32_e32 v44, v31
	v_mov_b32_e32 v45, v35
	v_mov_b32_e32 v42, v30
	v_mov_b32_e32 v43, v34
	v_pk_mul_f32 v[44:45], v[44:45], v[44:45]
	v_mov_b32_e32 v38, v32
	v_mov_b32_e32 v39, v36
	v_pk_fma_f32 v[42:43], v[42:43], v[42:43], v[44:45]
	v_mov_b32_e32 v40, v33
	v_mov_b32_e32 v41, v37
	v_pk_fma_f32 v[38:39], v[38:39], v[38:39], v[42:43]
	s_nop 0
	v_pk_fma_f32 v[46:47], v[40:41], v[40:41], v[38:39]
	v_add_f32_e32 v19, v46, v47
	v_mov_b32_e32 v54, v57
	v_mov_b32_e32 v55, v61
	v_mov_b32_e32 v52, v56
	v_mov_b32_e32 v53, v60
	v_pk_mul_f32 v[54:55], v[54:55], v[54:55]
	v_mov_b32_e32 v48, v58
	v_mov_b32_e32 v49, v62
	v_pk_fma_f32 v[52:53], v[52:53], v[52:53], v[54:55]
	v_mov_b32_e32 v50, v59
	v_mov_b32_e32 v51, v63
	v_pk_fma_f32 v[48:49], v[48:49], v[48:49], v[52:53]
	s_nop 0
	v_pk_fma_f32 v[48:49], v[50:51], v[50:51], v[48:49]
	s_nop 0
	v_add_f32_e32 v19, v19, v48
	v_add_f32_e32 v19, v19, v49
	ds_bpermute_b32 v29, v0, v19
	s_waitcnt lgkmcnt(0)
	v_add_f32_e32 v19, v19, v29
	ds_bpermute_b32 v29, v24, v19
	s_waitcnt lgkmcnt(0)
	v_add_f32_e32 v19, v19, v29
	ds_bpermute_b32 v29, v25, v19
	s_waitcnt lgkmcnt(0)
	v_add_f32_e32 v19, v19, v29
	ds_bpermute_b32 v29, v26, v19
	s_waitcnt lgkmcnt(0)
	v_add_f32_e32 v19, v19, v29
	ds_bpermute_b32 v29, v27, v19
	s_waitcnt lgkmcnt(0)
	v_add_f32_e32 v19, v19, v29
	ds_bpermute_b32 v29, v28, v19
	s_waitcnt lgkmcnt(0)
	v_add_f32_e32 v19, v19, v29
	v_fmamk_f32 v19, v19, 0x3a800000, v169
	v_cmp_gt_f32_e32 vcc, s33, v19
	v_mul_f32_e32 v29, 0x4b800000, v19
	s_nop 0
	v_cndmask_b32_e32 v19, v19, v29, vcc
	v_rsq_f32_e32 v19, v19
	s_nop 0
	v_mul_f32_e32 v29, 0x45800000, v19
	v_cndmask_b32_e32 v46, v19, v29, vcc
	v_pk_mul_f32 v[30:31], v[30:31], v[46:47] op_sel_hi:[1,0]
	v_pk_mul_f32 v[32:33], v[32:33], v[46:47] op_sel_hi:[1,0]
	v_pk_mul_f32 v[30:31], v[2:3], v[30:31]
	v_pk_mul_f32 v[32:33], v[4:5], v[32:33]
	v_cvt_pk_bf16_f32 v30, v30, v31
	v_cvt_pk_bf16_f32 v31, v32, v33
	global_store_dwordx2 v[20:21], v[30:31], off
	v_pk_mul_f32 v[30:31], v[34:35], v[46:47] op_sel_hi:[1,0]
	v_pk_mul_f32 v[32:33], v[36:37], v[46:47] op_sel_hi:[1,0]
	v_pk_mul_f32 v[30:31], v[6:7], v[30:31]
	v_pk_mul_f32 v[32:33], v[8:9], v[32:33]
	v_cvt_pk_bf16_f32 v30, v30, v31
	v_cvt_pk_bf16_f32 v31, v32, v33
	global_store_dwordx2 v[20:21], v[30:31], off offset:512
	v_pk_mul_f32 v[30:31], v[56:57], v[46:47] op_sel_hi:[1,0]
	v_pk_mul_f32 v[32:33], v[58:59], v[46:47] op_sel_hi:[1,0]
	v_pk_mul_f32 v[30:31], v[10:11], v[30:31]
	v_pk_mul_f32 v[32:33], v[12:13], v[32:33]
	v_cvt_pk_bf16_f32 v30, v30, v31
	v_cvt_pk_bf16_f32 v31, v32, v33
	global_store_dwordx2 v[20:21], v[30:31], off offset:1024
	v_pk_mul_f32 v[30:31], v[60:61], v[46:47] op_sel_hi:[1,0]
	v_pk_mul_f32 v[32:33], v[62:63], v[46:47] op_sel_hi:[1,0]
	v_pk_mul_f32 v[30:31], v[14:15], v[30:31]
	v_pk_mul_f32 v[32:33], v[16:17], v[32:33]
	v_cvt_pk_bf16_f32 v30, v30, v31
	v_cvt_pk_bf16_f32 v31, v32, v33
	v_cmp_lt_i32_e32 vcc, s59, v18
	global_store_dwordx2 v[20:21], v[30:31], off offset:1536
	v_lshl_add_u64 v[20:21], v[20:21], 0, s[6:7]
	s_or_b64 s[10:11], vcc, s[10:11]
	s_waitcnt vmcnt(4)
	v_mov_b64_e32 v[30:31], v[64:65]
	v_mov_b64_e32 v[32:33], v[66:67]
	v_mov_b64_e32 v[34:35], v[68:69]
	v_mov_b64_e32 v[36:37], v[70:71]
	v_mov_b64_e32 v[56:57], v[72:73]
	v_mov_b64_e32 v[58:59], v[74:75]
	v_mov_b64_e32 v[60:61], v[76:77]
	v_mov_b64_e32 v[62:63], v[78:79]
	s_andn2_b64 exec, exec, s[10:11]
	s_cbranch_execnz .LBB0_81

; __device__ __forceinline__ int TID() { int t = threadIdx.x; asm volatile("" : "+v"(t)); return t; }
; __device__ __forceinline__ int BID() { int t = blockIdx.x; asm volatile("" : "+s"(t)); return t; }
; __device__ __forceinline__ int NBLK() { int t = gridDim.x; asm volatile("" : "+s"(t)); return t; }
; __device__ void rmsnorm_phase(const float* __restrict__ x, const float* __restrict__ g, bf16_t* h, float* outf) {
;     const int lane = TID() & 63, gw = BID() * 8 + (TID() >> 6), nw = NBLK() * 8;
;     float4 gv[4];
; #pragma unroll
;     for (int i = 0; i < 4; ++i) gv[i] = ((const float4*)g)[lane + 64 * i];
;     for (int row = gw; row < T_; row += nw) {
;         const float4* xr = (const float4*)(x + (size_t)row * D_);
;         float4 v[4]; float ss = 0.f;
; #pragma unroll
;         for (int i = 0; i < 4; ++i) { v[i] = xr[lane + 64 * i]; ss += v[i].x * v[i].x + v[i].y * v[i].y + v[i].z * v[i].z + v[i].w * v[i].w; }
.LBB0_223:
	s_mov_b32 s4, 5
	v_mov_b32_e32 v0, v168
	s_mov_b32 s2, s73
	v_mov_b32_e32 v2, v168
	s_mov_b32 s6, s39
	v_ashrrev_i32_e32 v2, 6, v2
	v_lshl_add_u32 v18, s2, 3, v2
	v_cmp_gt_i32_e32 vcc, s58, v18
	s_and_saveexec_b64 s[2:3], vcc
	s_cbranch_execz .LBB0_226
	s_ashr_i32 s5, s4, 31
	s_lshl_b64 s[4:5], s[4:5], 3
	s_add_u32 s4, s0, s4
	s_addc_u32 s5, s1, s5
	s_load_dwordx2 s[4:5], s[4:5], 0x0
	v_readlane_b32 s8, v254, 31
	v_readlane_b32 s9, v254, 32
	s_lshl_b64 s[8:9], s[8:9], 12
	v_and_b32_e32 v22, 63, v0
	s_waitcnt lgkmcnt(0)
	s_add_u32 s4, s4, s8
	v_lshlrev_b32_e32 v29, 4, v22
	s_addc_u32 s5, s5, s9
	global_load_dwordx4 v[2:5], v29, s[4:5]
	global_load_dwordx4 v[6:9], v29, s[4:5] offset:1024
	global_load_dwordx4 v[10:13], v29, s[4:5] offset:2048
	global_load_dwordx4 v[14:17], v29, s[4:5] offset:3072
	v_and_b32_e32 v0, 64, v174
	v_add_u32_e32 v19, 64, v0
	v_xor_b32_e32 v0, 32, v174
	v_cmp_lt_i32_e32 vcc, v0, v19
	v_xor_b32_e32 v20, 16, v174
	s_lshl_b32 s4, s6, 3
	v_cndmask_b32_e32 v0, v174, v0, vcc
	v_cmp_lt_i32_e32 vcc, v20, v19
	v_readlane_b32 s6, v254, 33
	v_readlane_b32 s7, v254, 34
	v_cndmask_b32_e32 v20, v174, v20, vcc
	v_lshlrev_b32_e32 v24, 2, v20
	v_xor_b32_e32 v20, 8, v174
	v_cmp_lt_i32_e32 vcc, v20, v19
	s_ashr_i32 s5, s4, 31
	v_lshlrev_b32_e32 v0, 2, v0
	v_cndmask_b32_e32 v20, v174, v20, vcc
	v_lshlrev_b32_e32 v25, 2, v20
	v_xor_b32_e32 v20, 4, v174
	v_cmp_lt_i32_e32 vcc, v20, v19
	s_lshl_b64 s[8:9], s[4:5], 12
	s_mov_b64 s[10:11], 0
	v_cndmask_b32_e32 v20, v174, v20, vcc
	v_lshlrev_b32_e32 v26, 2, v20
	v_xor_b32_e32 v20, 2, v174
	v_cmp_lt_i32_e32 vcc, v20, v19
	s_nop 1
	v_cndmask_b32_e32 v20, v174, v20, vcc
	v_lshlrev_b32_e32 v27, 2, v20
	v_xor_b32_e32 v20, 1, v174
	v_cmp_lt_i32_e32 vcc, v20, v19
	s_nop 1
	v_cndmask_b32_e32 v19, v174, v20, vcc
	v_lshlrev_b32_e32 v28, 2, v19
	v_ashrrev_i32_e32 v19, 31, v18
	v_lshlrev_b64 v[20:21], 11, v[18:19]
	v_lshl_or_b32 v20, v22, 3, v20
	v_lshlrev_b64 v[22:23], 12, v[18:19]
	v_or_b32_e32 v22, v22, v29
	v_lshl_add_u64 v[20:21], s[6:7], 0, v[20:21]
	s_lshl_b64 s[6:7], s[4:5], 11
	v_lshl_add_u64 v[22:23], s[78:79], 0, v[22:23]
	v_readfirstlane_b32 s5, v18
	global_load_dwordx4 v[30:33], v[22:23], off
	global_load_dwordx4 v[34:37], v[22:23], off offset:1024
	global_load_dwordx4 v[56:59], v[22:23], off offset:2048
	global_load_dwordx4 v[60:63], v[22:23], off offset:3072
	v_lshl_add_u64 v[22:23], v[22:23], 0, s[8:9]

; __device__ __forceinline__ int TID() { int t = threadIdx.x; asm volatile("" : "+v"(t)); return t; }
; __device__ __forceinline__ int BID() { int t = blockIdx.x; asm volatile("" : "+s"(t)); return t; }
; __device__ __forceinline__ int NBLK() { int t = gridDim.x; asm volatile("" : "+s"(t)); return t; }
; __device__ void rmsnorm_phase(const float* __restrict__ x, const float* __restrict__ g, bf16_t* h, float* outf) {
;     const int lane = TID() & 63, gw = BID() * 8 + (TID() >> 6), nw = NBLK() * 8;
;     float4 gv[4];
; #pragma unroll
;     for (int i = 0; i < 4; ++i) gv[i] = ((const float4*)g)[lane + 64 * i];
;     for (int row = gw; row < T_; row += nw) {
;         const float4* xr = (const float4*)(x + (size_t)row * D_);
;         float4 v[4]; float ss = 0.f;
; #pragma unroll
;         for (int i = 0; i < 4; ++i) { v[i] = xr[lane + 64 * i]; ss += v[i].x * v[i].x + v[i].y * v[i].y + v[i].z * v[i].z + v[i].w * v[i].w; }
.LBB0_599:
	s_and_b64 vcc, exec, s[2:3]
	s_cbranch_vccz .LBB0_604
	s_mov_b32 s4, 5
	v_mov_b32_e32 v0, v168
	s_mov_b32 s2, s73
	v_mov_b32_e32 v2, v168
	s_mov_b32 s6, s39
	v_ashrrev_i32_e32 v2, 6, v2
	s_waitcnt vmcnt(0)
	v_lshl_add_u32 v18, s2, 3, v2
	v_cmp_gt_i32_e32 vcc, s58, v18
	s_and_saveexec_b64 s[2:3], vcc
	s_cbranch_execz .LBB0_603
	s_ashr_i32 s5, s4, 31
	s_lshl_b64 s[4:5], s[4:5], 3
	s_add_u32 s4, s0, s4
	s_addc_u32 s5, s1, s5
	s_load_dwordx2 s[4:5], s[4:5], 0x0
	v_readlane_b32 s8, v254, 31
	v_readlane_b32 s9, v254, 32
	s_mov_b32 s10, s8
	s_ashr_i32 s11, s8, 31
	v_writelane_b32 v254, s8, 31
	v_and_b32_e32 v22, 63, v0
	v_lshlrev_b32_e32 v29, 4, v22
	v_writelane_b32 v254, s9, 32
	s_lshl_b64 s[8:9], s[10:11], 12
	s_waitcnt lgkmcnt(0)
	s_add_u32 s4, s4, s8
	s_addc_u32 s5, s5, s9
	global_load_dwordx4 v[2:5], v29, s[4:5]
	global_load_dwordx4 v[6:9], v29, s[4:5] offset:1024
	global_load_dwordx4 v[10:13], v29, s[4:5] offset:2048
	global_load_dwordx4 v[14:17], v29, s[4:5] offset:3072
	v_and_b32_e32 v0, 64, v174
	v_add_u32_e32 v19, 64, v0
	v_xor_b32_e32 v0, 32, v174
	v_cmp_lt_i32_e32 vcc, v0, v19
	v_xor_b32_e32 v20, 16, v174
	s_lshl_b32 s4, s6, 3
	v_cndmask_b32_e32 v0, v174, v0, vcc
	v_cmp_lt_i32_e32 vcc, v20, v19
	v_readlane_b32 s6, v254, 33
	v_readlane_b32 s7, v254, 34
	v_cndmask_b32_e32 v20, v174, v20, vcc
	v_lshlrev_b32_e32 v24, 2, v20
	v_xor_b32_e32 v20, 8, v174
	v_cmp_lt_i32_e32 vcc, v20, v19
	s_ashr_i32 s5, s4, 31
	v_lshlrev_b32_e32 v0, 2, v0
	v_cndmask_b32_e32 v20, v174, v20, vcc
	v_lshlrev_b32_e32 v25, 2, v20
	v_xor_b32_e32 v20, 4, v174
	v_cmp_lt_i32_e32 vcc, v20, v19
	s_lshl_b64 s[8:9], s[4:5], 12
	s_mov_b64 s[10:11], 0
	v_cndmask_b32_e32 v20, v174, v20, vcc
	v_lshlrev_b32_e32 v26, 2, v20
	v_xor_b32_e32 v20, 2, v174
	v_cmp_lt_i32_e32 vcc, v20, v19
	s_nop 1
	v_cndmask_b32_e32 v20, v174, v20, vcc
	v_lshlrev_b32_e32 v27, 2, v20
	v_xor_b32_e32 v20, 1, v174
	v_cmp_lt_i32_e32 vcc, v20, v19
	s_nop 1
	v_cndmask_b32_e32 v19, v174, v20, vcc
	v_lshlrev_b32_e32 v28, 2, v19
	v_ashrrev_i32_e32 v19, 31, v18
	v_lshlrev_b64 v[20:21], 11, v[18:19]
	v_lshl_or_b32 v20, v22, 3, v20
	v_lshlrev_b64 v[22:23], 12, v[18:19]
	v_or_b32_e32 v22, v22, v29
	v_lshl_add_u64 v[20:21], s[6:7], 0, v[20:21]
	s_lshl_b64 s[6:7], s[4:5], 11
	v_lshl_add_u64 v[22:23], s[78:79], 0, v[22:23]
	v_readfirstlane_b32 s5, v18
	global_load_dwordx4 v[30:33], v[22:23], off
	global_load_dwordx4 v[34:37], v[22:23], off offset:1024
	global_load_dwordx4 v[56:59], v[22:23], off offset:2048
	global_load_dwordx4 v[60:63], v[22:23], off offset:3072
	v_lshl_add_u64 v[22:23], v[22:23], 0, s[8:9]
